# phase-0 transpose items re-dealt 16 per adaLN workgroup / 36 per free workgroup
# speedup vs baseline: 1.0093x; 1.0093x over previous
.LBB0_29:
	s_lshr_b32 s94, s93, 6
	s_lshl_b32 s0, s24, 3
	s_add_i32 s8, s0, s94
	s_lshl_b32 s3, s56, 3
	s_lshl_b32 s66, s56, 9
	s_add_u32 s6, s54, 0x500000
	s_addc_u32 s7, s55, 0
	s_add_u32 s64, s54, 0x900000
	s_addc_u32 s65, s55, 0
	s_add_u32 s60, s54, 0xb00000
	s_addc_u32 s61, s55, 0
	s_add_u32 s50, s54, 0x1300000
	s_addc_u32 s51, s55, 0
	s_cmp_lt_i32 s40, 1
	v_writelane_b32 v246, s24, 6
	s_cselect_b64 s[4:5], -1, 0
	s_cmp_gt_i32 s40, 0
	v_writelane_b32 v246, s0, 7
	s_cselect_b64 s[0:1], -1, 0
	s_cmp_lt_i32 s41, 1
	s_cselect_b64 s[10:11], -1, 0
	s_or_b64 s[0:1], s[10:11], s[0:1]
	s_and_b64 vcc, exec, s[0:1]
	s_cbranch_vccnz .LBB0_71
	v_mov_b32_e32 v1, 0
	v_mbcnt_lo_u32_b32 v163, -1, 0
	v_mbcnt_hi_u32_b32 v163, -1, v163
	global_load_dwordx2 v[2:3], v1, s[96:97] offset:112 sc0
	global_load_dwordx2 v[4:5], v1, s[96:97] offset:144 sc0
	global_load_dwordx2 v[6:7], v1, s[96:97] offset:96 sc0
	global_load_dwordx2 v[8:9], v1, s[96:97] offset:104 sc0
	s_cmpk_gt_i32 s8, 0x14ff
	s_waitcnt vmcnt(3)
	v_readfirstlane_b32 s13, v3
	v_readfirstlane_b32 s12, v2
	s_waitcnt vmcnt(2)
	v_readfirstlane_b32 s11, v5
	v_readfirstlane_b32 s10, v4
	s_waitcnt vmcnt(1)
	v_readfirstlane_b32 s15, v7
	v_readfirstlane_b32 s14, v6
	s_waitcnt vmcnt(0)
	v_readfirstlane_b32 s17, v9
	v_readfirstlane_b32 s16, v8
	v_lshrrev_b32_e32 v3, 3, v163
	v_and_b32_e32 v2, 7, v163
	v_lshlrev_b32_e32 v4, 4, v2
	s_lshl_b32 s18, s94, 14
	v_mul_u32_u24_e32 v5, 33, v3
	v_lshl_add_u32 v5, v2, 2, v5
	v_lshl_add_u32 v5, v5, 2, s18
	v_mul_u32_u24_e32 v6, 0x108, v2
	v_add_u32_e32 v6, v6, v3
	v_lshl_add_u32 v6, v6, 2, s18
	s_lshr_b32 s18, s8, 3
	s_cmp_lg_u32 s56, 0x100
	s_cbranch_scc1 .Ltr_generic
	s_cmp_lt_u32 s18, 0xc0
	s_cbranch_scc0 .Ltr_free
	s_mul_i32 s0, s18, 16
	s_add_i32 s9, s0, 16
	s_branch .Ltr_dealt
.Ltr_free:
	s_sub_i32 s18, s18, 0xc0
	s_mul_i32 s0, s18, 36
	s_addk_i32 s0, 0xc00
	s_add_i32 s9, s0, 36
